# job3 loop PV: transposed V fragment reads six MFMAs ahead (two extra 4-register buffers) instead of four
# baseline (speedup 1.0000x reference)
.Lj3ld_norka:
	s_or_b64 exec, exec, s[6:7]
	s_waitcnt lgkmcnt(0)
	v_mfma_f32_32x32x16_bf16 v[130:145], v[232:235], v[236:239], v[130:145]
	s_nop 11
	v_mov_b32_e32 v146, v130
	v_mov_b32_e32 v147, v131
	v_max_f32_e32 v130, v146, v147
	v_max3_f32 v130, v130, v132, v133
	v_max3_f32 v130, v130, v134, v135
	v_max3_f32 v130, v130, v136, v137
	v_max3_f32 v130, v130, v138, v139
	v_max3_f32 v130, v130, v140, v141
	v_max3_f32 v130, v130, v142, v143
	v_max3_f32 v130, v130, v144, v145
	v_sub_f32_e32 v131, v230, v130
	v_cmp_gt_f32_e32 vcc, 0xc2200000, v131
	s_cbranch_vccnz .Llazy0_full
	ds_read_b64_tr_b16 v[232:233], v222
	ds_read_b64_tr_b16 v[234:235], v222 offset:4736
	ds_read_b64_tr_b16 v[236:237], v222 offset:64
	ds_read_b64_tr_b16 v[238:239], v222 offset:4800
	ds_read_b64_tr_b16 v[240:241], v222 offset:128
	ds_read_b64_tr_b16 v[242:243], v222 offset:4864
	ds_read_b64_tr_b16 v[246:247], v222 offset:192
	ds_read_b64_tr_b16 v[248:249], v222 offset:4928
	ds_read_b64_tr_b16 v[152:153], v222 offset:256
	ds_read_b64_tr_b16 v[154:155], v222 offset:4992
	ds_read_b64_tr_b16 v[156:157], v222 offset:320
	ds_read_b64_tr_b16 v[158:159], v222 offset:5056
	v_mov_b32_e32 v229, v230
	v_mov_b32_e32 v130, 1.0
	s_branch .LBB0_946
.Llazy0_full:
	v_mbcnt_hi_u32_b32 v131, -1, v217
	v_and_b32_e32 v149, 64, v131
	v_xor_b32_e32 v148, 32, v131
	v_add_u32_e32 v149, 64, v149
	v_cmp_lt_i32_e32 vcc, v148, v149
	s_nop 1
	v_cndmask_b32_e32 v131, v131, v148, vcc
	v_lshlrev_b32_e32 v131, 2, v131
	ds_bpermute_b32 v131, v131, v130
	s_waitcnt lgkmcnt(0)
	ds_read_b64_tr_b16 v[232:233], v222
	ds_read_b64_tr_b16 v[234:235], v222 offset:4736
	ds_read_b64_tr_b16 v[236:237], v222 offset:64
	ds_read_b64_tr_b16 v[238:239], v222 offset:4800
	ds_read_b64_tr_b16 v[240:241], v222 offset:128
	ds_read_b64_tr_b16 v[242:243], v222 offset:4864
	ds_read_b64_tr_b16 v[246:247], v222 offset:192
	ds_read_b64_tr_b16 v[248:249], v222 offset:4928
	ds_read_b64_tr_b16 v[152:153], v222 offset:256
	ds_read_b64_tr_b16 v[154:155], v222 offset:4992
	ds_read_b64_tr_b16 v[156:157], v222 offset:320
	ds_read_b64_tr_b16 v[158:159], v222 offset:5056
	v_max3_f32 v229, v230, v130, v131
	v_sub_f32_e32 v130, v230, v229
	v_exp_f32_e32 v130, v130
	s_nop 0
	v_cmp_neq_f32_e32 vcc, 1.0, v130
	s_cbranch_vccz .LBB0_946
	v_pk_mul_f32 v[128:129], v[128:129], v[130:131] op_sel_hi:[1,0]
	v_pk_mul_f32 v[126:127], v[126:127], v[130:131] op_sel_hi:[1,0]
	v_pk_mul_f32 v[124:125], v[124:125], v[130:131] op_sel_hi:[1,0]
	v_pk_mul_f32 v[122:123], v[122:123], v[130:131] op_sel_hi:[1,0]
	v_pk_mul_f32 v[120:121], v[120:121], v[130:131] op_sel_hi:[1,0]
	v_pk_mul_f32 v[118:119], v[118:119], v[130:131] op_sel_hi:[1,0]
	v_pk_mul_f32 v[116:117], v[116:117], v[130:131] op_sel_hi:[1,0]
	v_pk_mul_f32 v[114:115], v[114:115], v[130:131] op_sel_hi:[1,0]
	v_pk_mul_f32 v[112:113], v[112:113], v[130:131] op_sel_hi:[1,0]
	v_pk_mul_f32 v[110:111], v[110:111], v[130:131] op_sel_hi:[1,0]
	v_pk_mul_f32 v[108:109], v[108:109], v[130:131] op_sel_hi:[1,0]
	v_pk_mul_f32 v[106:107], v[106:107], v[130:131] op_sel_hi:[1,0]
	v_pk_mul_f32 v[104:105], v[104:105], v[130:131] op_sel_hi:[1,0]
	v_pk_mul_f32 v[102:103], v[102:103], v[130:131] op_sel_hi:[1,0]
	v_pk_mul_f32 v[100:101], v[100:101], v[130:131] op_sel_hi:[1,0]
	v_pk_mul_f32 v[98:99], v[98:99], v[130:131] op_sel_hi:[1,0]
	v_pk_mul_f32 v[96:97], v[96:97], v[130:131] op_sel_hi:[1,0]
	v_pk_mul_f32 v[94:95], v[94:95], v[130:131] op_sel_hi:[1,0]
	v_pk_mul_f32 v[92:93], v[92:93], v[130:131] op_sel_hi:[1,0]
	v_pk_mul_f32 v[90:91], v[90:91], v[130:131] op_sel_hi:[1,0]
	v_pk_mul_f32 v[88:89], v[88:89], v[130:131] op_sel_hi:[1,0]
	v_pk_mul_f32 v[86:87], v[86:87], v[130:131] op_sel_hi:[1,0]
	v_pk_mul_f32 v[84:85], v[84:85], v[130:131] op_sel_hi:[1,0]
	v_pk_mul_f32 v[82:83], v[82:83], v[130:131] op_sel_hi:[1,0]
	v_pk_mul_f32 v[80:81], v[80:81], v[130:131] op_sel_hi:[1,0]
	v_pk_mul_f32 v[78:79], v[78:79], v[130:131] op_sel_hi:[1,0]
	v_pk_mul_f32 v[76:77], v[76:77], v[130:131] op_sel_hi:[1,0]
	v_pk_mul_f32 v[74:75], v[74:75], v[130:131] op_sel_hi:[1,0]
	v_pk_mul_f32 v[72:73], v[72:73], v[130:131] op_sel_hi:[1,0]
	v_pk_mul_f32 v[70:71], v[70:71], v[130:131] op_sel_hi:[1,0]
	v_pk_mul_f32 v[68:69], v[68:69], v[130:131] op_sel_hi:[1,0]
	v_pk_mul_f32 v[66:67], v[66:67], v[130:131] op_sel_hi:[1,0]
	v_pk_mul_f32 v[64:65], v[64:65], v[130:131] op_sel_hi:[1,0]
	v_pk_mul_f32 v[62:63], v[62:63], v[130:131] op_sel_hi:[1,0]
	v_pk_mul_f32 v[60:61], v[60:61], v[130:131] op_sel_hi:[1,0]
	v_pk_mul_f32 v[58:59], v[58:59], v[130:131] op_sel_hi:[1,0]
	v_pk_mul_f32 v[56:57], v[56:57], v[130:131] op_sel_hi:[1,0]
	v_pk_mul_f32 v[54:55], v[54:55], v[130:131] op_sel_hi:[1,0]
	v_pk_mul_f32 v[52:53], v[52:53], v[130:131] op_sel_hi:[1,0]
	v_pk_mul_f32 v[50:51], v[50:51], v[130:131] op_sel_hi:[1,0]
	v_pk_mul_f32 v[48:49], v[48:49], v[130:131] op_sel_hi:[1,0]
	v_pk_mul_f32 v[46:47], v[46:47], v[130:131] op_sel_hi:[1,0]
	v_pk_mul_f32 v[44:45], v[44:45], v[130:131] op_sel_hi:[1,0]
	v_pk_mul_f32 v[42:43], v[42:43], v[130:131] op_sel_hi:[1,0]
	v_pk_mul_f32 v[40:41], v[40:41], v[130:131] op_sel_hi:[1,0]
	v_pk_mul_f32 v[38:39], v[38:39], v[130:131] op_sel_hi:[1,0]
	v_pk_mul_f32 v[36:37], v[36:37], v[130:131] op_sel_hi:[1,0]
	v_pk_mul_f32 v[34:35], v[34:35], v[130:131] op_sel_hi:[1,0]
	v_pk_mul_f32 v[32:33], v[32:33], v[130:131] op_sel_hi:[1,0]
	v_pk_mul_f32 v[30:31], v[30:31], v[130:131] op_sel_hi:[1,0]
	v_pk_mul_f32 v[28:29], v[28:29], v[130:131] op_sel_hi:[1,0]
	v_pk_mul_f32 v[26:27], v[26:27], v[130:131] op_sel_hi:[1,0]
	v_pk_mul_f32 v[24:25], v[24:25], v[130:131] op_sel_hi:[1,0]
	v_pk_mul_f32 v[22:23], v[22:23], v[130:131] op_sel_hi:[1,0]
	v_pk_mul_f32 v[20:21], v[20:21], v[130:131] op_sel_hi:[1,0]
	v_pk_mul_f32 v[18:19], v[18:19], v[130:131] op_sel_hi:[1,0]
	v_pk_mul_f32 v[16:17], v[16:17], v[130:131] op_sel_hi:[1,0]
	v_pk_mul_f32 v[14:15], v[14:15], v[130:131] op_sel_hi:[1,0]
	v_pk_mul_f32 v[12:13], v[12:13], v[130:131] op_sel_hi:[1,0]
	v_pk_mul_f32 v[10:11], v[10:11], v[130:131] op_sel_hi:[1,0]
	v_pk_mul_f32 v[8:9], v[8:9], v[130:131] op_sel_hi:[1,0]
	v_pk_mul_f32 v[6:7], v[6:7], v[130:131] op_sel_hi:[1,0]
	v_pk_mul_f32 v[4:5], v[4:5], v[130:131] op_sel_hi:[1,0]
	v_pk_mul_f32 v[2:3], v[2:3], v[130:131] op_sel_hi:[1,0]
.LBB0_946:
	v_sub_f32_e32 v131, v146, v229
	v_exp_f32_e32 v131, v131
	v_sub_f32_e32 v147, v147, v229
	v_exp_f32_e32 v147, v147
	v_sub_f32_e32 v132, v132, v229
	v_exp_f32_e32 v132, v132
	v_sub_f32_e32 v133, v133, v229
	v_exp_f32_e32 v133, v133
	v_sub_f32_e32 v134, v134, v229
	v_add_f32_e32 v146, 0, v131
	v_exp_f32_e32 v148, v134
	v_add_f32_e32 v146, v147, v146
	v_add_f32_e32 v146, v132, v146
	v_sub_f32_e32 v135, v135, v229
	v_add_f32_e32 v146, v133, v146
	v_exp_f32_e32 v135, v135
	v_sub_f32_e32 v136, v136, v229
	v_add_f32_e32 v134, v148, v146
	v_exp_f32_e32 v146, v136
	v_sub_f32_e32 v136, v137, v229
	v_exp_f32_e32 v149, v136
	v_sub_f32_e32 v136, v138, v229
	v_exp_f32_e32 v150, v136
	v_sub_f32_e32 v136, v139, v229
	v_add_f32_e32 v134, v135, v134
	v_exp_f32_e32 v151, v136
	v_sub_f32_e32 v136, v140, v229
	v_add_f32_e32 v134, v146, v134
	v_exp_f32_e32 v140, v136
	v_sub_f32_e32 v136, v141, v229
	v_add_f32_e32 v134, v149, v134
	v_exp_f32_e32 v141, v136
	v_sub_f32_e32 v136, v142, v229
	v_add_f32_e32 v134, v150, v134
	v_exp_f32_e32 v142, v136
	v_sub_f32_e32 v136, v143, v229
	v_add_f32_e32 v134, v151, v134
	v_exp_f32_e32 v143, v136
	v_add_f32_e32 v134, v140, v134
	v_add_f32_e32 v134, v141, v134
	v_sub_f32_e32 v136, v144, v229
	v_add_f32_e32 v134, v142, v134
	v_exp_f32_e32 v144, v136
	v_sub_f32_e32 v136, v145, v229
	v_add_f32_e32 v134, v143, v134
	v_exp_f32_e32 v145, v136
	v_cvt_pk_bf16_f32 v136, v131, v147
	v_cvt_pk_bf16_f32 v137, v132, v133
	v_cvt_pk_bf16_f32 v131, v140, v141
	v_cvt_pk_bf16_f32 v132, v142, v143
	v_cvt_pk_bf16_f32 v138, v148, v135
	v_cvt_pk_bf16_f32 v139, v146, v149
	v_add_f32_e32 v134, v144, v134
	v_add_f32_e32 v134, v145, v134
	s_waitcnt lgkmcnt(10)
	v_mfma_f32_32x32x16_bf16 v[114:129], v[232:235], v[136:139], v[114:129]
	ds_read_b64_tr_b16 v[232:233], v222 offset:384
	ds_read_b64_tr_b16 v[234:235], v222 offset:5120
	v_fmac_f32_e32 v134, v211, v130
	v_cvt_pk_bf16_f32 v130, v150, v151
	v_cvt_pk_bf16_f32 v133, v144, v145
	v_mov_b32_e32 v211, v134
	s_waitcnt lgkmcnt(10)
	v_mfma_f32_32x32x16_bf16 v[98:113], v[236:239], v[136:139], v[98:113]
	ds_read_b64_tr_b16 v[236:237], v222 offset:448
	ds_read_b64_tr_b16 v[238:239], v222 offset:5184
	s_waitcnt lgkmcnt(10)
	v_mfma_f32_32x32x16_bf16 v[82:97], v[240:243], v[136:139], v[82:97]
	ds_read_b64_tr_b16 v[240:241], v222 offset:9472
	ds_read_b64_tr_b16 v[242:243], v222 offset:14208
	s_waitcnt lgkmcnt(10)
	v_mfma_f32_32x32x16_bf16 v[66:81], v[246:249], v[136:139], v[66:81]
	ds_read_b64_tr_b16 v[246:247], v222 offset:9536
	ds_read_b64_tr_b16 v[248:249], v222 offset:14272
	s_waitcnt lgkmcnt(10)
	v_mfma_f32_32x32x16_bf16 v[50:65], v[152:155], v[136:139], v[50:65]
	ds_read_b64_tr_b16 v[152:153], v222 offset:9600
	ds_read_b64_tr_b16 v[154:155], v222 offset:14336
	s_waitcnt lgkmcnt(10)
	v_mfma_f32_32x32x16_bf16 v[34:49], v[156:159], v[136:139], v[34:49]
	ds_read_b64_tr_b16 v[156:157], v222 offset:9664
	ds_read_b64_tr_b16 v[158:159], v222 offset:14400
	s_waitcnt lgkmcnt(10)
	v_mfma_f32_32x32x16_bf16 v[18:33], v[232:235], v[136:139], v[18:33]
	ds_read_b64_tr_b16 v[232:233], v222 offset:9728
	ds_read_b64_tr_b16 v[234:235], v222 offset:14464
	s_waitcnt lgkmcnt(10)
	v_mfma_f32_32x32x16_bf16 v[2:17], v[236:239], v[136:139], v[2:17]
	ds_read_b64_tr_b16 v[236:237], v222 offset:9792
	ds_read_b64_tr_b16 v[238:239], v222 offset:14528
	s_waitcnt lgkmcnt(10)
	v_mfma_f32_32x32x16_bf16 v[114:129], v[240:243], v[130:133], v[114:129]
	ds_read_b64_tr_b16 v[240:241], v222 offset:9856
	ds_read_b64_tr_b16 v[242:243], v222 offset:14592
	s_waitcnt lgkmcnt(10)
	v_mfma_f32_32x32x16_bf16 v[98:113], v[246:249], v[130:133], v[98:113]
	ds_read_b64_tr_b16 v[246:247], v222 offset:9920
	ds_read_b64_tr_b16 v[248:249], v222 offset:14656
	s_waitcnt lgkmcnt(10)
	v_mfma_f32_32x32x16_bf16 v[82:97], v[152:155], v[130:133], v[82:97]
	s_waitcnt lgkmcnt(8)
	v_mfma_f32_32x32x16_bf16 v[66:81], v[156:159], v[130:133], v[66:81]
	s_waitcnt lgkmcnt(6)
	v_mfma_f32_32x32x16_bf16 v[50:65], v[232:235], v[130:133], v[50:65]
	s_waitcnt lgkmcnt(4)
	v_mfma_f32_32x32x16_bf16 v[34:49], v[236:239], v[130:133], v[34:49]
	s_waitcnt lgkmcnt(2)
	v_mfma_f32_32x32x16_bf16 v[18:33], v[240:243], v[130:133], v[18:33]
	s_waitcnt lgkmcnt(0)
	v_mfma_f32_32x32x16_bf16 v[2:17], v[246:249], v[130:133], v[2:17]
	s_branch .LBB0_948
